# plus mix_scan recurrence loop: the 16 chunk loads of a trip issued up front before the sequential state update (same arithmetic and order)
# speedup vs baseline: 1.0192x; 1.0019x over previous
; DEVI float bf2f(u16 b) { return __uint_as_float(((unsigned)b) << 16); }
; DEVI u32x2 pk4(f32x4 v) { u32x2 r; r.x = cvt_pk(v[0], v[1]); r.y = cvt_pk(v[2], v[3]); return r; }
; DEVI void mix_scan_phase(const MixArgs a, bool with_n) {
;     ...
;     for (int e = gt; e < 16 * 256 * 32; e += nthr) { const int dk4 = (e & 31) * 4, dv = (e >> 5) & 255, bh = e >> 13;
;         f32x4 run = (f32x4){0.f, 0.f, 0.f, 0.f};
; #pragma unroll 16
;         for (int c = 0; c < NCH; ++c) { const size_t it = (size_t)bh * NCH + c; u16* sp = a.states + (it * 256 + dv) * 128 + dk4;
;             const f32x4 d = *(const f32x4*)(a.dec + it * 128 + dk4); const bf16x4 x = *(const bf16x4*)sp;
;             *(u32x2*)sp = pk4(run);
; #pragma unroll
;             for (int j = 0; j < 4; ++j) run[j] = d[j] * run[j] + bf2f((u16)x[j]); } }
.LBB0_627:
	v_lshl_add_u64 v[6:7], s[20:21], 0, v[0:1]
	v_add_co_u32_e32 v10, vcc, 0x1d600000, v6
	v_lshl_add_u64 v[4:5], s[20:21], 0, v[2:3]
	s_nop 0
	v_addc_co_u32_e32 v11, vcc, 0, v7, vcc
	v_add_co_u32_e32 v4, vcc, 0x19380000, v4
	s_mov_b64 s[0:1], 0x10000
	s_nop 0
	v_addc_co_u32_e32 v5, vcc, 0, v5, vcc
	v_add_co_u32_e32 v6, vcc, 0x1000, v10
	v_mov_b64_e32 v[24:25], v[4:5]
	v_mov_b64_e32 v[26:27], v[4:5]
	v_addc_co_u32_e32 v7, vcc, 0, v11, vcc
	global_load_dwordx4 v[56:59], v[10:11], off
	global_load_dwordx2 v[134:135], v[24:25], off
	v_lshl_add_u64 v[24:25], v[24:25], 0, s[0:1]
	global_load_dwordx4 v[60:63], v[10:11], off offset:512
	global_load_dwordx2 v[136:137], v[24:25], off
	v_lshl_add_u64 v[24:25], v[24:25], 0, s[0:1]
	global_load_dwordx4 v[64:67], v[10:11], off offset:1024
	global_load_dwordx2 v[138:139], v[24:25], off
	v_lshl_add_u64 v[24:25], v[24:25], 0, s[0:1]
	global_load_dwordx4 v[68:71], v[10:11], off offset:1536
	global_load_dwordx2 v[140:141], v[24:25], off
	v_lshl_add_u64 v[24:25], v[24:25], 0, s[0:1]
	global_load_dwordx4 v[72:75], v[10:11], off offset:2048
	global_load_dwordx2 v[142:143], v[24:25], off
	v_lshl_add_u64 v[24:25], v[24:25], 0, s[0:1]
	global_load_dwordx4 v[76:79], v[10:11], off offset:2560
	global_load_dwordx2 v[144:145], v[24:25], off
	v_lshl_add_u64 v[24:25], v[24:25], 0, s[0:1]
	global_load_dwordx4 v[80:83], v[10:11], off offset:3072
	global_load_dwordx2 v[148:149], v[24:25], off
	v_lshl_add_u64 v[24:25], v[24:25], 0, s[0:1]
	global_load_dwordx4 v[88:91], v[10:11], off offset:3584
	global_load_dwordx2 v[150:151], v[24:25], off
	v_lshl_add_u64 v[24:25], v[24:25], 0, s[0:1]
	global_load_dwordx4 v[92:95], v[6:7], off
	global_load_dwordx2 v[152:153], v[24:25], off
	v_lshl_add_u64 v[24:25], v[24:25], 0, s[0:1]
	global_load_dwordx4 v[100:103], v[6:7], off offset:512
	global_load_dwordx2 v[162:163], v[24:25], off
	v_lshl_add_u64 v[24:25], v[24:25], 0, s[0:1]
	global_load_dwordx4 v[104:107], v[6:7], off offset:1024
	global_load_dwordx2 v[164:165], v[24:25], off
	v_lshl_add_u64 v[24:25], v[24:25], 0, s[0:1]
	global_load_dwordx4 v[108:111], v[6:7], off offset:1536
	global_load_dwordx2 v[176:177], v[24:25], off
	v_lshl_add_u64 v[24:25], v[24:25], 0, s[0:1]
	global_load_dwordx4 v[112:115], v[6:7], off offset:2048
	global_load_dwordx2 v[178:179], v[24:25], off
	v_lshl_add_u64 v[24:25], v[24:25], 0, s[0:1]
	global_load_dwordx4 v[116:119], v[6:7], off offset:2560
	global_load_dwordx2 v[180:181], v[24:25], off
	v_lshl_add_u64 v[24:25], v[24:25], 0, s[0:1]
	global_load_dwordx4 v[126:129], v[6:7], off offset:3072
	global_load_dwordx2 v[182:183], v[24:25], off
	v_lshl_add_u64 v[24:25], v[24:25], 0, s[0:1]
	global_load_dwordx4 v[130:133], v[6:7], off offset:3584
	global_load_dwordx2 v[120:121], v[24:25], off
	v_cvt_pk_bf16_f32 v28, v12, v13
	v_cvt_pk_bf16_f32 v29, v14, v15
	global_store_dwordx2 v[26:27], v[28:29], off
	v_lshl_add_u64 v[26:27], v[26:27], 0, s[0:1]
	s_waitcnt vmcnt(31)
	v_and_b32_e32 v21, 0xffff0000, v134
	v_lshlrev_b32_e32 v20, 16, v134
	v_and_b32_e32 v23, 0xffff0000, v135
	v_lshlrev_b32_e32 v22, 16, v135
	v_pk_fma_f32 v[12:13], v[12:13], v[56:57], v[20:21]
	v_pk_fma_f32 v[14:15], v[14:15], v[58:59], v[22:23]
	v_cvt_pk_bf16_f32 v28, v12, v13
	v_cvt_pk_bf16_f32 v29, v14, v15
	global_store_dwordx2 v[26:27], v[28:29], off
	v_lshl_add_u64 v[26:27], v[26:27], 0, s[0:1]
	s_waitcnt vmcnt(30)
	v_and_b32_e32 v21, 0xffff0000, v136
	v_lshlrev_b32_e32 v20, 16, v136
	v_and_b32_e32 v23, 0xffff0000, v137
	v_lshlrev_b32_e32 v22, 16, v137
	v_pk_fma_f32 v[12:13], v[12:13], v[60:61], v[20:21]
	v_pk_fma_f32 v[14:15], v[14:15], v[62:63], v[22:23]
	v_cvt_pk_bf16_f32 v28, v12, v13
	v_cvt_pk_bf16_f32 v29, v14, v15
	global_store_dwordx2 v[26:27], v[28:29], off
	v_lshl_add_u64 v[26:27], v[26:27], 0, s[0:1]
	s_waitcnt vmcnt(29)
	v_and_b32_e32 v21, 0xffff0000, v138
	v_lshlrev_b32_e32 v20, 16, v138
	v_and_b32_e32 v23, 0xffff0000, v139
	v_lshlrev_b32_e32 v22, 16, v139
	v_pk_fma_f32 v[12:13], v[12:13], v[64:65], v[20:21]
	v_pk_fma_f32 v[14:15], v[14:15], v[66:67], v[22:23]
	v_cvt_pk_bf16_f32 v28, v12, v13
	v_cvt_pk_bf16_f32 v29, v14, v15
	global_store_dwordx2 v[26:27], v[28:29], off
	v_lshl_add_u64 v[26:27], v[26:27], 0, s[0:1]
	s_waitcnt vmcnt(28)
	v_and_b32_e32 v21, 0xffff0000, v140
	v_lshlrev_b32_e32 v20, 16, v140
	v_and_b32_e32 v23, 0xffff0000, v141
	v_lshlrev_b32_e32 v22, 16, v141
	v_pk_fma_f32 v[12:13], v[12:13], v[68:69], v[20:21]
	v_pk_fma_f32 v[14:15], v[14:15], v[70:71], v[22:23]
	v_cvt_pk_bf16_f32 v28, v12, v13
	v_cvt_pk_bf16_f32 v29, v14, v15
	global_store_dwordx2 v[26:27], v[28:29], off
	v_lshl_add_u64 v[26:27], v[26:27], 0, s[0:1]
	s_waitcnt vmcnt(27)
	v_and_b32_e32 v21, 0xffff0000, v142
	v_lshlrev_b32_e32 v20, 16, v142
	v_and_b32_e32 v23, 0xffff0000, v143
	v_lshlrev_b32_e32 v22, 16, v143
	v_pk_fma_f32 v[12:13], v[12:13], v[72:73], v[20:21]
	v_pk_fma_f32 v[14:15], v[14:15], v[74:75], v[22:23]
	v_cvt_pk_bf16_f32 v28, v12, v13
	v_cvt_pk_bf16_f32 v29, v14, v15
	global_store_dwordx2 v[26:27], v[28:29], off
	v_lshl_add_u64 v[26:27], v[26:27], 0, s[0:1]
	s_waitcnt vmcnt(26)
; DEVI float bf2f(u16 b) { return __uint_as_float(((unsigned)b) << 16); }
; DEVI u32x2 pk4(f32x4 v) { u32x2 r; r.x = cvt_pk(v[0], v[1]); r.y = cvt_pk(v[2], v[3]); return r; }
; DEVI void mix_scan_phase(const MixArgs a, bool with_n) {
;     ...
;     for (int e = gt; e < 16 * 256 * 32; e += nthr) { const int dk4 = (e & 31) * 4, dv = (e >> 5) & 255, bh = e >> 13;
;         f32x4 run = (f32x4){0.f, 0.f, 0.f, 0.f};
; #pragma unroll 16
;         for (int c = 0; c < NCH; ++c) { const size_t it = (size_t)bh * NCH + c; u16* sp = a.states + (it * 256 + dv) * 128 + dk4;
;             const f32x4 d = *(const f32x4*)(a.dec + it * 128 + dk4); const bf16x4 x = *(const bf16x4*)sp;
;             *(u32x2*)sp = pk4(run);
; #pragma unroll
;             for (int j = 0; j < 4; ++j) run[j] = d[j] * run[j] + bf2f((u16)x[j]); } }
	v_and_b32_e32 v21, 0xffff0000, v144
	v_lshlrev_b32_e32 v20, 16, v144
	v_and_b32_e32 v23, 0xffff0000, v145
	v_lshlrev_b32_e32 v22, 16, v145
	v_pk_fma_f32 v[12:13], v[12:13], v[76:77], v[20:21]
	v_pk_fma_f32 v[14:15], v[14:15], v[78:79], v[22:23]
	v_cvt_pk_bf16_f32 v28, v12, v13
	v_cvt_pk_bf16_f32 v29, v14, v15
	global_store_dwordx2 v[26:27], v[28:29], off
	v_lshl_add_u64 v[26:27], v[26:27], 0, s[0:1]
	s_waitcnt vmcnt(25)
	v_and_b32_e32 v21, 0xffff0000, v148
	v_lshlrev_b32_e32 v20, 16, v148
	v_and_b32_e32 v23, 0xffff0000, v149
	v_lshlrev_b32_e32 v22, 16, v149
	v_pk_fma_f32 v[12:13], v[12:13], v[80:81], v[20:21]
	v_pk_fma_f32 v[14:15], v[14:15], v[82:83], v[22:23]
	v_cvt_pk_bf16_f32 v28, v12, v13
	v_cvt_pk_bf16_f32 v29, v14, v15
	global_store_dwordx2 v[26:27], v[28:29], off
	v_lshl_add_u64 v[26:27], v[26:27], 0, s[0:1]
	s_waitcnt vmcnt(24)
	v_and_b32_e32 v21, 0xffff0000, v150
	v_lshlrev_b32_e32 v20, 16, v150
	v_and_b32_e32 v23, 0xffff0000, v151
	v_lshlrev_b32_e32 v22, 16, v151
	v_pk_fma_f32 v[12:13], v[12:13], v[88:89], v[20:21]
	v_pk_fma_f32 v[14:15], v[14:15], v[90:91], v[22:23]
	v_cvt_pk_bf16_f32 v28, v12, v13
	v_cvt_pk_bf16_f32 v29, v14, v15
	global_store_dwordx2 v[26:27], v[28:29], off
	v_lshl_add_u64 v[26:27], v[26:27], 0, s[0:1]
	s_waitcnt vmcnt(23)
	v_and_b32_e32 v21, 0xffff0000, v152
	v_lshlrev_b32_e32 v20, 16, v152
	v_and_b32_e32 v23, 0xffff0000, v153
	v_lshlrev_b32_e32 v22, 16, v153
	v_pk_fma_f32 v[12:13], v[12:13], v[92:93], v[20:21]
	v_pk_fma_f32 v[14:15], v[14:15], v[94:95], v[22:23]
	v_cvt_pk_bf16_f32 v28, v12, v13
	v_cvt_pk_bf16_f32 v29, v14, v15
	global_store_dwordx2 v[26:27], v[28:29], off
	v_lshl_add_u64 v[26:27], v[26:27], 0, s[0:1]
	s_waitcnt vmcnt(22)
	v_and_b32_e32 v21, 0xffff0000, v162
	v_lshlrev_b32_e32 v20, 16, v162
	v_and_b32_e32 v23, 0xffff0000, v163
	v_lshlrev_b32_e32 v22, 16, v163
	v_pk_fma_f32 v[12:13], v[12:13], v[100:101], v[20:21]
	v_pk_fma_f32 v[14:15], v[14:15], v[102:103], v[22:23]
	v_cvt_pk_bf16_f32 v28, v12, v13
	v_cvt_pk_bf16_f32 v29, v14, v15
	global_store_dwordx2 v[26:27], v[28:29], off
	v_lshl_add_u64 v[26:27], v[26:27], 0, s[0:1]
	s_waitcnt vmcnt(21)
	v_and_b32_e32 v21, 0xffff0000, v164
	v_lshlrev_b32_e32 v20, 16, v164
	v_and_b32_e32 v23, 0xffff0000, v165
	v_lshlrev_b32_e32 v22, 16, v165
	v_pk_fma_f32 v[12:13], v[12:13], v[104:105], v[20:21]
	v_pk_fma_f32 v[14:15], v[14:15], v[106:107], v[22:23]
	v_cvt_pk_bf16_f32 v28, v12, v13
	v_cvt_pk_bf16_f32 v29, v14, v15
	global_store_dwordx2 v[26:27], v[28:29], off
	v_lshl_add_u64 v[26:27], v[26:27], 0, s[0:1]
	s_waitcnt vmcnt(20)
	v_and_b32_e32 v21, 0xffff0000, v176
	v_lshlrev_b32_e32 v20, 16, v176
	v_and_b32_e32 v23, 0xffff0000, v177
	v_lshlrev_b32_e32 v22, 16, v177
	v_pk_fma_f32 v[12:13], v[12:13], v[108:109], v[20:21]
	v_pk_fma_f32 v[14:15], v[14:15], v[110:111], v[22:23]
	v_cvt_pk_bf16_f32 v28, v12, v13
	v_cvt_pk_bf16_f32 v29, v14, v15
	global_store_dwordx2 v[26:27], v[28:29], off
	v_lshl_add_u64 v[26:27], v[26:27], 0, s[0:1]
	s_waitcnt vmcnt(19)
	v_and_b32_e32 v21, 0xffff0000, v178
	v_lshlrev_b32_e32 v20, 16, v178
	v_and_b32_e32 v23, 0xffff0000, v179
	v_lshlrev_b32_e32 v22, 16, v179
	v_pk_fma_f32 v[12:13], v[12:13], v[112:113], v[20:21]
	v_pk_fma_f32 v[14:15], v[14:15], v[114:115], v[22:23]
	v_cvt_pk_bf16_f32 v28, v12, v13
	v_cvt_pk_bf16_f32 v29, v14, v15
	global_store_dwordx2 v[26:27], v[28:29], off
	v_lshl_add_u64 v[26:27], v[26:27], 0, s[0:1]
	s_waitcnt vmcnt(18)
	v_and_b32_e32 v21, 0xffff0000, v180
	v_lshlrev_b32_e32 v20, 16, v180
	v_and_b32_e32 v23, 0xffff0000, v181
	v_lshlrev_b32_e32 v22, 16, v181
	v_pk_fma_f32 v[12:13], v[12:13], v[116:117], v[20:21]
	v_pk_fma_f32 v[14:15], v[14:15], v[118:119], v[22:23]
	v_cvt_pk_bf16_f32 v28, v12, v13
	v_cvt_pk_bf16_f32 v29, v14, v15
	global_store_dwordx2 v[26:27], v[28:29], off
	v_lshl_add_u64 v[26:27], v[26:27], 0, s[0:1]
	s_waitcnt vmcnt(17)
	v_and_b32_e32 v21, 0xffff0000, v182
	v_lshlrev_b32_e32 v20, 16, v182
	v_and_b32_e32 v23, 0xffff0000, v183
	v_lshlrev_b32_e32 v22, 16, v183
	v_pk_fma_f32 v[12:13], v[12:13], v[126:127], v[20:21]
	v_pk_fma_f32 v[14:15], v[14:15], v[128:129], v[22:23]
	v_cvt_pk_bf16_f32 v28, v12, v13
	v_cvt_pk_bf16_f32 v29, v14, v15
	global_store_dwordx2 v[26:27], v[28:29], off
	s_waitcnt vmcnt(16)
	v_and_b32_e32 v21, 0xffff0000, v120
	v_lshlrev_b32_e32 v20, 16, v120
	v_and_b32_e32 v23, 0xffff0000, v121
	v_lshlrev_b32_e32 v22, 16, v121
	v_pk_fma_f32 v[12:13], v[12:13], v[130:131], v[20:21]
	v_pk_fma_f32 v[14:15], v[14:15], v[132:133], v[22:23]
	s_add_i32 s6, s6, -16
	v_lshl_add_u64 v[0:1], v[0:1], 0, s[74:75]
	s_mov_b64 s[0:1], 0x100000
	v_lshl_add_u64 v[2:3], v[2:3], 0, s[0:1]
	s_cmp_eq_u32 s6, 0
	s_cbranch_scc0 .LBB0_627
	v_add_u32_e32 v18, s40, v18
	s_mov_b32 s0, 0x1ffff
	v_cmp_lt_i32_e32 vcc, s0, v18
	v_readlane_b32 s0, v253, 52
	s_or_b64 s[4:5], vcc, s[4:5]
	s_nop 0
	v_add_u32_e32 v17, s0, v17
	s_andn2_b64 exec, exec, s[4:5]
	s_cbranch_execnz .LBB0_626
